# strategy 4: one static s_setprio 1 for waves 4-7 across the MLA and NA phase (reset to 0 at phase end)
# speedup vs baseline: 1.0112x; 1.0112x over previous
.LBB0_1348:
	s_or_b64 exec, exec, s[0:1]
	v_readlane_b32 s0, v246, 5
	s_and_b32 s3, s2, 7
	s_ashr_i32 s21, s0, 3
	s_ashr_i32 s20, s2, 3
	s_mul_i32 s0, s3, s21
	s_add_i32 s28, s0, s20
	s_cmpk_gt_i32 s28, 0x3ff
	s_waitcnt lgkmcnt(0)
	s_barrier
	v_readlane_b32 s1, v246, 6
	s_cbranch_scc1 .LBB0_1382
	v_readfirstlane_b32 s98, v162
	s_nop 3
	s_cmp_ge_u32 s98, 0x100
	s_cbranch_scc0 .Lp7_prio_done
	s_setprio 1
.Lp7_prio_done:
	v_mbcnt_hi_u32_b32 v164, -1, v163
	s_brev_b32 s4, 1
	v_and_b32_e32 v0, 64, v164
	s_mov_b32 s5, s4
	s_add_u32 s10, s64, 0xaa00000
	s_movk_i32 s24, 0xff80
	v_add_u32_e32 v166, 64, v0
	s_mov_b32 s6, s4
	s_mov_b32 s7, s4
	v_mov_b64_e32 v[0:1], s[4:5]
	s_mov_b32 s12, 0x3f803f80
	s_addc_u32 s11, s65, 0
	s_mov_b32 s17, 0
	v_mov_b32_e32 v145, 0
	s_movk_i32 s29, 0x600
	s_mov_b32 s30, 0x2aaaaaab
	s_movk_i32 s31, 0xff
	s_movk_i32 s33, 0x100
	s_movk_i32 s34, 0x70
	s_movk_i32 s35, 0xa0
	s_mov_b32 s25, -1
	v_xor_b32_e32 v165, 16, v164
	v_xor_b32_e32 v167, 32, v164
	v_mov_b64_e32 v[2:3], s[6:7]
	s_mov_b32 s13, s12
	s_mov_b32 s14, s12
	s_mov_b32 s15, s12
	s_mov_b32 s36, 0x41000000
	v_not_b32_e32 v168, 63
	s_mov_b32 s0, s28
	s_mov_b32 s37, 0
	s_branch .LBB0_1351

.LBB0_1410:
	s_setprio 0
	s_waitcnt vmcnt(0)
	s_barrier
	s_and_saveexec_b64 s[0:1], s[66:67]
	s_cbranch_execz .LBB0_1462
	v_mov_b32_e32 v0, 0x26b80
	s_waitcnt vmcnt(0) expcnt(0) lgkmcnt(0)
	ds_read_b32 v2, v0
	v_mov_b32_e32 v0, 0x26b84
	ds_read_b32 v0, v0
	s_waitcnt lgkmcnt(1)
	v_cmp_ne_u32_e32 vcc, 0, v2
	s_cbranch_vccnz .LBB0_1426
	v_readlane_b32 s4, v246, 5
	v_readlane_b32 s3, v247, 0
	v_readlane_b32 s5, v246, 6
	s_mul_i32 s3, s5, s3
	s_mul_i32 s3, s3, s4
	s_add_u32 s4, s38, 0x1000
	s_addc_u32 s5, s39, 0
	s_add_u32 s6, s38, 0x1100
	s_addc_u32 s7, s39, 0
	s_add_u32 s8, s38, 0x1200
	s_addc_u32 s9, s39, 0
	s_add_u32 s10, s38, 0x1300
	s_addc_u32 s11, s39, 0
	s_mov_b32 s18, 1
	v_mov_b32_e32 v16, 0
	s_branch .LBB0_1414
